# GEMM tile prologues: accumulators zeroed with 64 v_mov_b64 instead of 127 v_mov_b32
# speedup vs baseline: 1.0103x; 1.0006x over previous
; DI void gemm_phase(LAS unsigned char* lds, const Gemm g, const StaticOrder& S, const Epi& E) {
;     ...
;         for (int a = 0; a < 2; ++a)
; #pragma unroll
;             for (int b = 0; b < 2; ++b)
; #pragma unroll
;                 for (int m = 0; m < 4; ++m)
; #pragma unroll
;                     for (int n = 0; n < 2; ++n) acc[a][b][m][n] = (f32x4){0.f, 0.f, 0.f, 0.f};
.LBB0_176:
	s_ashr_i32 s23, s22, 31
	s_lshl_b64 s[24:25], s[22:23], 20
	s_add_u32 s24, s62, s24
	s_addc_u32 s25, s63, s25
	s_and_b64 s[26:27], s[2:3], exec
	s_cselect_b32 s5, s25, s31
	s_cselect_b32 s23, s24, s30
	s_ashr_i32 s21, s20, 31
	s_lshl_b64 s[26:27], s[20:21], 20
	s_add_u32 s26, s0, s26
	s_addc_u32 s27, s1, s27
	s_and_b64 s[38:39], s[2:3], exec
	s_cselect_b32 s21, s27, s35
	s_cselect_b32 s29, s26, s34
	s_add_u32 s30, s30, 0x80080
	s_addc_u32 s31, s31, 0
	s_add_u32 s54, s34, 0x100
	v_mov_b32_e32 v0, 0
	s_addc_u32 s55, s35, 0
	s_mov_b32 s56, -2
	v_mov_b64_e32 v[0:1], 0
	v_mov_b64_e32 v[2:3], 0
	v_mov_b64_e32 v[4:5], 0
	v_mov_b64_e32 v[6:7], 0
	v_mov_b64_e32 v[8:9], 0
	v_mov_b64_e32 v[10:11], 0
	v_mov_b64_e32 v[12:13], 0
	v_mov_b64_e32 v[14:15], 0
	v_mov_b64_e32 v[16:17], 0
	v_mov_b64_e32 v[18:19], 0
	v_mov_b64_e32 v[20:21], 0
	v_mov_b64_e32 v[22:23], 0
	v_mov_b64_e32 v[24:25], 0
	v_mov_b64_e32 v[26:27], 0
	v_mov_b64_e32 v[28:29], 0
	v_mov_b64_e32 v[30:31], 0
	v_mov_b64_e32 v[32:33], 0
	v_mov_b64_e32 v[34:35], 0
	v_mov_b64_e32 v[36:37], 0
	v_mov_b64_e32 v[38:39], 0
	v_mov_b64_e32 v[40:41], 0
	v_mov_b64_e32 v[42:43], 0
	v_mov_b64_e32 v[44:45], 0
	v_mov_b64_e32 v[46:47], 0
	v_mov_b64_e32 v[48:49], 0
	v_mov_b64_e32 v[50:51], 0
	v_mov_b64_e32 v[52:53], 0
	v_mov_b64_e32 v[54:55], 0
	v_mov_b64_e32 v[56:57], 0
	v_mov_b64_e32 v[58:59], 0
	v_mov_b64_e32 v[60:61], 0
	v_mov_b64_e32 v[62:63], 0
	v_mov_b64_e32 v[64:65], 0
	v_mov_b64_e32 v[66:67], 0
	v_mov_b64_e32 v[68:69], 0
	v_mov_b64_e32 v[70:71], 0
	v_mov_b64_e32 v[72:73], 0
	v_mov_b64_e32 v[74:75], 0
	v_mov_b64_e32 v[76:77], 0
	v_mov_b64_e32 v[78:79], 0
	v_mov_b64_e32 v[80:81], 0
	v_mov_b64_e32 v[82:83], 0
	v_mov_b64_e32 v[84:85], 0
	v_mov_b64_e32 v[86:87], 0
	v_mov_b64_e32 v[88:89], 0
	v_mov_b64_e32 v[90:91], 0
	v_mov_b64_e32 v[92:93], 0
	v_mov_b64_e32 v[94:95], 0
	v_mov_b64_e32 v[96:97], 0
	v_mov_b64_e32 v[98:99], 0
	v_mov_b64_e32 v[100:101], 0
	v_mov_b64_e32 v[102:103], 0
	v_mov_b64_e32 v[104:105], 0
	v_mov_b64_e32 v[106:107], 0
	v_mov_b64_e32 v[108:109], 0
	v_mov_b64_e32 v[110:111], 0
	v_mov_b64_e32 v[112:113], 0
	v_mov_b64_e32 v[114:115], 0
	v_mov_b64_e32 v[116:117], 0
	v_mov_b64_e32 v[118:119], 0
	v_mov_b64_e32 v[120:121], 0
	v_mov_b64_e32 v[122:123], 0
	v_mov_b64_e32 v[124:125], 0
	v_mov_b64_e32 v[126:127], 0
	s_cmp_eq_u32 s4, 10
	s_cselect_b64 vcc, -1, 0

; DI void gemm_phase(LAS unsigned char* lds, const Gemm g, const StaticOrder& S, const Epi& E) {
;     ...
;         for (int a = 0; a < 2; ++a)
; #pragma unroll
;             for (int b = 0; b < 2; ++b)
; #pragma unroll
;                 for (int m = 0; m < 4; ++m)
; #pragma unroll
;                     for (int n = 0; n < 2; ++n) acc[a][b][m][n] = (f32x4){0.f, 0.f, 0.f, 0.f};
.LBB0_342:
	s_ashr_i32 s25, s24, 31
	s_lshl_b64 s[28:29], s[24:25], 18
	s_add_u32 s28, s0, s28
	s_addc_u32 s29, s1, s29
	s_and_b64 s[4:5], s[4:5], exec
	s_cselect_b32 s25, s29, s51
	s_cselect_b32 s31, s28, s50
	s_add_u32 s68, s50, 0x100
	v_mov_b32_e32 v0, 0
	s_addc_u32 s69, s51, 0
	s_mov_b32 s70, -2
	v_mov_b64_e32 v[0:1], 0
	v_mov_b64_e32 v[2:3], 0
	v_mov_b64_e32 v[4:5], 0
	v_mov_b64_e32 v[6:7], 0
	v_mov_b64_e32 v[8:9], 0
	v_mov_b64_e32 v[10:11], 0
	v_mov_b64_e32 v[12:13], 0
	v_mov_b64_e32 v[14:15], 0
	v_mov_b64_e32 v[16:17], 0
	v_mov_b64_e32 v[18:19], 0
	v_mov_b64_e32 v[20:21], 0
	v_mov_b64_e32 v[22:23], 0
	v_mov_b64_e32 v[24:25], 0
	v_mov_b64_e32 v[26:27], 0
	v_mov_b64_e32 v[28:29], 0
	v_mov_b64_e32 v[30:31], 0
	v_mov_b64_e32 v[32:33], 0
	v_mov_b64_e32 v[34:35], 0
	v_mov_b64_e32 v[36:37], 0
	v_mov_b64_e32 v[38:39], 0
	v_mov_b64_e32 v[40:41], 0
	v_mov_b64_e32 v[42:43], 0
	v_mov_b64_e32 v[44:45], 0
	v_mov_b64_e32 v[46:47], 0
	v_mov_b64_e32 v[48:49], 0
	v_mov_b64_e32 v[50:51], 0
	v_mov_b64_e32 v[52:53], 0
	v_mov_b64_e32 v[54:55], 0
	v_mov_b64_e32 v[56:57], 0
	v_mov_b64_e32 v[58:59], 0
	v_mov_b64_e32 v[60:61], 0
	v_mov_b64_e32 v[62:63], 0
	v_mov_b64_e32 v[64:65], 0
	v_mov_b64_e32 v[66:67], 0
	v_mov_b64_e32 v[68:69], 0
	v_mov_b64_e32 v[70:71], 0
	v_mov_b64_e32 v[72:73], 0
	v_mov_b64_e32 v[74:75], 0
	v_mov_b64_e32 v[76:77], 0
	v_mov_b64_e32 v[78:79], 0
	v_mov_b64_e32 v[80:81], 0
	v_mov_b64_e32 v[82:83], 0
	v_mov_b64_e32 v[84:85], 0
	v_mov_b64_e32 v[86:87], 0
	v_mov_b64_e32 v[88:89], 0
	v_mov_b64_e32 v[90:91], 0
	v_mov_b64_e32 v[92:93], 0
	v_mov_b64_e32 v[94:95], 0
	v_mov_b64_e32 v[96:97], 0
	v_mov_b64_e32 v[98:99], 0
	v_mov_b64_e32 v[100:101], 0
	v_mov_b64_e32 v[102:103], 0
	v_mov_b64_e32 v[104:105], 0
	v_mov_b64_e32 v[106:107], 0
	v_mov_b64_e32 v[108:109], 0
	v_mov_b64_e32 v[110:111], 0
	v_mov_b64_e32 v[112:113], 0
	v_mov_b64_e32 v[114:115], 0
	v_mov_b64_e32 v[116:117], 0
	v_mov_b64_e32 v[118:119], 0
	v_mov_b64_e32 v[120:121], 0
	v_mov_b64_e32 v[122:123], 0
	v_mov_b64_e32 v[124:125], 0
	v_mov_b64_e32 v[126:127], 0

; DI void gemm_phase(LAS unsigned char* lds, const Gemm g, const StaticOrder& S, const Epi& E) {
;     ...
;         for (int a = 0; a < 2; ++a)
; #pragma unroll
;             for (int b = 0; b < 2; ++b)
; #pragma unroll
;                 for (int m = 0; m < 4; ++m)
; #pragma unroll
;                     for (int n = 0; n < 2; ++n) acc[a][b][m][n] = (f32x4){0.f, 0.f, 0.f, 0.f};
.LBB0_402:
	s_ashr_i32 s21, s20, 31
	s_lshl_b64 s[24:25], s[20:21], 17
	s_add_u32 s24, s12, s24
	s_addc_u32 s25, s13, s25
	s_and_b64 s[6:7], s[6:7], exec
	v_mov_b32_e32 v0, 0
	s_cselect_b32 s21, s25, s29
	s_cselect_b32 s27, s24, s28
	s_mov_b32 s46, 0
	s_mov_b64 s[6:7], -1
	s_mov_b64 s[34:35], 0
	v_mov_b64_e32 v[0:1], 0
	v_mov_b64_e32 v[2:3], 0
	v_mov_b64_e32 v[4:5], 0
	v_mov_b64_e32 v[6:7], 0
	v_mov_b64_e32 v[8:9], 0
	v_mov_b64_e32 v[10:11], 0
	v_mov_b64_e32 v[12:13], 0
	v_mov_b64_e32 v[14:15], 0
	v_mov_b64_e32 v[16:17], 0
	v_mov_b64_e32 v[18:19], 0
	v_mov_b64_e32 v[20:21], 0
	v_mov_b64_e32 v[22:23], 0
	v_mov_b64_e32 v[24:25], 0
	v_mov_b64_e32 v[26:27], 0
	v_mov_b64_e32 v[28:29], 0
	v_mov_b64_e32 v[30:31], 0
	v_mov_b64_e32 v[32:33], 0
	v_mov_b64_e32 v[34:35], 0
	v_mov_b64_e32 v[36:37], 0
	v_mov_b64_e32 v[38:39], 0
	v_mov_b64_e32 v[40:41], 0
	v_mov_b64_e32 v[42:43], 0
	v_mov_b64_e32 v[44:45], 0
	v_mov_b64_e32 v[46:47], 0
	v_mov_b64_e32 v[48:49], 0
	v_mov_b64_e32 v[50:51], 0
	v_mov_b64_e32 v[52:53], 0
	v_mov_b64_e32 v[54:55], 0
	v_mov_b64_e32 v[56:57], 0
	v_mov_b64_e32 v[58:59], 0
	v_mov_b64_e32 v[60:61], 0
	v_mov_b64_e32 v[62:63], 0
	v_mov_b64_e32 v[64:65], 0
	v_mov_b64_e32 v[66:67], 0
	v_mov_b64_e32 v[68:69], 0
	v_mov_b64_e32 v[70:71], 0
	v_mov_b64_e32 v[72:73], 0
	v_mov_b64_e32 v[74:75], 0
	v_mov_b64_e32 v[76:77], 0
	v_mov_b64_e32 v[78:79], 0
	v_mov_b64_e32 v[80:81], 0
	v_mov_b64_e32 v[82:83], 0
	v_mov_b64_e32 v[84:85], 0
	v_mov_b64_e32 v[86:87], 0
	v_mov_b64_e32 v[88:89], 0
	v_mov_b64_e32 v[90:91], 0
	v_mov_b64_e32 v[92:93], 0
	v_mov_b64_e32 v[94:95], 0
	v_mov_b64_e32 v[96:97], 0
	v_mov_b64_e32 v[98:99], 0
	v_mov_b64_e32 v[100:101], 0
	v_mov_b64_e32 v[102:103], 0
	v_mov_b64_e32 v[104:105], 0
	v_mov_b64_e32 v[106:107], 0
	v_mov_b64_e32 v[108:109], 0
	v_mov_b64_e32 v[110:111], 0
	v_mov_b64_e32 v[112:113], 0
	v_mov_b64_e32 v[114:115], 0
	v_mov_b64_e32 v[116:117], 0
	v_mov_b64_e32 v[118:119], 0
	v_mov_b64_e32 v[120:121], 0
	v_mov_b64_e32 v[122:123], 0
	v_mov_b64_e32 v[124:125], 0
	v_mov_b64_e32 v[126:127], 0

; DI void gemm_phase(LAS unsigned char* lds, const Gemm g, const StaticOrder& S, const Epi& E) {
;     ...
;         for (int a = 0; a < 2; ++a)
; #pragma unroll
;             for (int b = 0; b < 2; ++b)
; #pragma unroll
;                 for (int m = 0; m < 4; ++m)
; #pragma unroll
;                     for (int n = 0; n < 2; ++n) acc[a][b][m][n] = (f32x4){0.f, 0.f, 0.f, 0.f};
.LBB0_460:
	s_ashr_i32 s21, s20, 31
	s_lshl_b64 s[24:25], s[20:21], 17
	s_add_u32 s24, s12, s24
	s_addc_u32 s25, s13, s25
	s_and_b64 s[4:5], s[4:5], exec
	v_mov_b32_e32 v0, 0
	s_cselect_b32 s21, s25, s31
	s_cselect_b32 s76, s24, s30
	s_mov_b32 s46, 0
	s_mov_b64 s[4:5], -1
	s_mov_b64 s[34:35], 0
	v_mov_b64_e32 v[0:1], 0
	v_mov_b64_e32 v[2:3], 0
	v_mov_b64_e32 v[4:5], 0
	v_mov_b64_e32 v[6:7], 0
	v_mov_b64_e32 v[8:9], 0
	v_mov_b64_e32 v[10:11], 0
	v_mov_b64_e32 v[12:13], 0
	v_mov_b64_e32 v[14:15], 0
	v_mov_b64_e32 v[16:17], 0
	v_mov_b64_e32 v[18:19], 0
	v_mov_b64_e32 v[20:21], 0
	v_mov_b64_e32 v[22:23], 0
	v_mov_b64_e32 v[24:25], 0
	v_mov_b64_e32 v[26:27], 0
	v_mov_b64_e32 v[28:29], 0
	v_mov_b64_e32 v[30:31], 0
	v_mov_b64_e32 v[32:33], 0
	v_mov_b64_e32 v[34:35], 0
	v_mov_b64_e32 v[36:37], 0
	v_mov_b64_e32 v[38:39], 0
	v_mov_b64_e32 v[40:41], 0
	v_mov_b64_e32 v[42:43], 0
	v_mov_b64_e32 v[44:45], 0
	v_mov_b64_e32 v[46:47], 0
	v_mov_b64_e32 v[48:49], 0
	v_mov_b64_e32 v[50:51], 0
	v_mov_b64_e32 v[52:53], 0
	v_mov_b64_e32 v[54:55], 0
	v_mov_b64_e32 v[56:57], 0
	v_mov_b64_e32 v[58:59], 0
	v_mov_b64_e32 v[60:61], 0
	v_mov_b64_e32 v[62:63], 0
	v_mov_b64_e32 v[64:65], 0
	v_mov_b64_e32 v[66:67], 0
	v_mov_b64_e32 v[68:69], 0
	v_mov_b64_e32 v[70:71], 0
	v_mov_b64_e32 v[72:73], 0
	v_mov_b64_e32 v[74:75], 0
	v_mov_b64_e32 v[76:77], 0
	v_mov_b64_e32 v[78:79], 0
	v_mov_b64_e32 v[80:81], 0
	v_mov_b64_e32 v[82:83], 0
	v_mov_b64_e32 v[84:85], 0
	v_mov_b64_e32 v[86:87], 0
	v_mov_b64_e32 v[88:89], 0
	v_mov_b64_e32 v[90:91], 0
	v_mov_b64_e32 v[92:93], 0
	v_mov_b64_e32 v[94:95], 0
	v_mov_b64_e32 v[96:97], 0
	v_mov_b64_e32 v[98:99], 0
	v_mov_b64_e32 v[100:101], 0
	v_mov_b64_e32 v[102:103], 0
	v_mov_b64_e32 v[104:105], 0
	v_mov_b64_e32 v[106:107], 0
	v_mov_b64_e32 v[108:109], 0
	v_mov_b64_e32 v[110:111], 0
	v_mov_b64_e32 v[112:113], 0
	v_mov_b64_e32 v[114:115], 0
	v_mov_b64_e32 v[116:117], 0
	v_mov_b64_e32 v[118:119], 0
	v_mov_b64_e32 v[120:121], 0
	v_mov_b64_e32 v[122:123], 0
	v_mov_b64_e32 v[124:125], 0
	v_mov_b64_e32 v[126:127], 0

; DI void gemm_phase(LAS unsigned char* lds, const Gemm g, const StaticOrder& S, const Epi& E) {
;     ...
;         for (int a = 0; a < 2; ++a)
; #pragma unroll
;             for (int b = 0; b < 2; ++b)
; #pragma unroll
;                 for (int m = 0; m < 4; ++m)
; #pragma unroll
;                     for (int n = 0; n < 2; ++n) acc[a][b][m][n] = (f32x4){0.f, 0.f, 0.f, 0.f};
.LBB0_570:
	s_ashr_i32 s27, s26, 31
	s_lshl_b64 s[28:29], s[26:27], 19
	s_add_u32 s28, s33, s28
	s_addc_u32 s29, s40, s29
	s_and_b64 s[46:47], s[30:31], exec
	s_cselect_b32 s76, s29, s55
	s_cselect_b32 s77, s28, s54
	s_add_u32 s78, s54, 0x100
	v_mov_b32_e32 v0, 0
	s_addc_u32 s79, s55, 0
	v_lshl_add_u64 v[146:147], s[54:55], 0, v[142:143]
	v_lshl_add_u64 v[148:149], s[54:55], 0, v[144:145]
	s_mov_b32 s80, -2
	s_mov_b64 s[54:55], 0
	v_mov_b64_e32 v[0:1], 0
	v_mov_b64_e32 v[2:3], 0
	v_mov_b64_e32 v[4:5], 0
	v_mov_b64_e32 v[6:7], 0
	v_mov_b64_e32 v[8:9], 0
	v_mov_b64_e32 v[10:11], 0
	v_mov_b64_e32 v[12:13], 0
	v_mov_b64_e32 v[14:15], 0
	v_mov_b64_e32 v[16:17], 0
	v_mov_b64_e32 v[18:19], 0
	v_mov_b64_e32 v[20:21], 0
	v_mov_b64_e32 v[22:23], 0
	v_mov_b64_e32 v[24:25], 0
	v_mov_b64_e32 v[26:27], 0
	v_mov_b64_e32 v[28:29], 0
	v_mov_b64_e32 v[30:31], 0
	v_mov_b64_e32 v[32:33], 0
	v_mov_b64_e32 v[34:35], 0
	v_mov_b64_e32 v[36:37], 0
	v_mov_b64_e32 v[38:39], 0
	v_mov_b64_e32 v[40:41], 0
	v_mov_b64_e32 v[42:43], 0
	v_mov_b64_e32 v[44:45], 0
	v_mov_b64_e32 v[46:47], 0
	v_mov_b64_e32 v[48:49], 0
	v_mov_b64_e32 v[50:51], 0
	v_mov_b64_e32 v[52:53], 0
	v_mov_b64_e32 v[54:55], 0
	v_mov_b64_e32 v[56:57], 0
	v_mov_b64_e32 v[58:59], 0
	v_mov_b64_e32 v[60:61], 0
	v_mov_b64_e32 v[62:63], 0
	v_mov_b64_e32 v[64:65], 0
	v_mov_b64_e32 v[66:67], 0
	v_mov_b64_e32 v[68:69], 0
	v_mov_b64_e32 v[70:71], 0
	v_mov_b64_e32 v[72:73], 0
	v_mov_b64_e32 v[74:75], 0
	v_mov_b64_e32 v[76:77], 0
	v_mov_b64_e32 v[78:79], 0
	v_mov_b64_e32 v[80:81], 0
	v_mov_b64_e32 v[82:83], 0
	v_mov_b64_e32 v[84:85], 0
	v_mov_b64_e32 v[86:87], 0
	v_mov_b64_e32 v[88:89], 0
	v_mov_b64_e32 v[90:91], 0
	v_mov_b64_e32 v[92:93], 0
	v_mov_b64_e32 v[94:95], 0
	v_mov_b64_e32 v[96:97], 0
	v_mov_b64_e32 v[98:99], 0
	v_mov_b64_e32 v[100:101], 0
	v_mov_b64_e32 v[102:103], 0
	v_mov_b64_e32 v[104:105], 0
	v_mov_b64_e32 v[106:107], 0
	v_mov_b64_e32 v[108:109], 0
	v_mov_b64_e32 v[110:111], 0
	v_mov_b64_e32 v[112:113], 0
	v_mov_b64_e32 v[114:115], 0
	v_mov_b64_e32 v[116:117], 0
	v_mov_b64_e32 v[118:119], 0
	v_mov_b64_e32 v[120:121], 0
	v_mov_b64_e32 v[122:123], 0
	v_mov_b64_e32 v[124:125], 0
	v_mov_b64_e32 v[126:127], 0

; DI void gemm_phase(LAS unsigned char* lds, const Gemm g, const StaticOrder& S, const Epi& E) {
;     ...
;         for (int a = 0; a < 2; ++a)
; #pragma unroll
;             for (int b = 0; b < 2; ++b)
; #pragma unroll
;                 for (int m = 0; m < 4; ++m)
; #pragma unroll
;                     for (int n = 0; n < 2; ++n) acc[a][b][m][n] = (f32x4){0.f, 0.f, 0.f, 0.f};
.LBB0_935:
	s_ashr_i32 s21, s20, 31
	s_lshl_b64 s[22:23], s[20:21], 20
	s_add_u32 s22, s53, s22
	s_addc_u32 s23, s54, s23
	s_and_b64 s[24:25], s[6:7], exec
	s_cselect_b32 s21, s23, s31
	s_cselect_b32 s27, s22, s30
	s_ashr_i32 s19, s18, 31
	s_lshl_b64 s[24:25], s[18:19], 20
	s_add_u32 s24, s0, s24
	s_addc_u32 s25, s1, s25
	s_and_b64 s[36:37], s[6:7], exec
	s_cselect_b32 s19, s25, s35
	s_cselect_b32 s48, s24, s34
	s_add_u32 s30, s30, 0x80080
	s_addc_u32 s31, s31, 0
	s_add_u32 s49, s34, 0x100
	v_mov_b32_e32 v0, 0
	s_addc_u32 s50, s35, 0
	s_mov_b32 s51, -2
	s_waitcnt lgkmcnt(0)
	v_mov_b64_e32 v[0:1], 0
	v_mov_b64_e32 v[2:3], 0
	v_mov_b64_e32 v[4:5], 0
	v_mov_b64_e32 v[6:7], 0
	v_mov_b64_e32 v[8:9], 0
	v_mov_b64_e32 v[10:11], 0
	v_mov_b64_e32 v[12:13], 0
	v_mov_b64_e32 v[14:15], 0
	v_mov_b64_e32 v[16:17], 0
	v_mov_b64_e32 v[18:19], 0
	v_mov_b64_e32 v[20:21], 0
	v_mov_b64_e32 v[22:23], 0
	v_mov_b64_e32 v[24:25], 0
	v_mov_b64_e32 v[26:27], 0
	v_mov_b64_e32 v[28:29], 0
	v_mov_b64_e32 v[30:31], 0
	v_mov_b64_e32 v[32:33], 0
	v_mov_b64_e32 v[34:35], 0
	v_mov_b64_e32 v[36:37], 0
	v_mov_b64_e32 v[38:39], 0
	v_mov_b64_e32 v[40:41], 0
	v_mov_b64_e32 v[42:43], 0
	v_mov_b64_e32 v[44:45], 0
	v_mov_b64_e32 v[46:47], 0
	v_mov_b64_e32 v[48:49], 0
	v_mov_b64_e32 v[50:51], 0
	v_mov_b64_e32 v[52:53], 0
	v_mov_b64_e32 v[54:55], 0
	v_mov_b64_e32 v[56:57], 0
	v_mov_b64_e32 v[58:59], 0
	v_mov_b64_e32 v[60:61], 0
	v_mov_b64_e32 v[62:63], 0
	v_mov_b64_e32 v[64:65], 0
	v_mov_b64_e32 v[66:67], 0
	v_mov_b64_e32 v[68:69], 0
	v_mov_b64_e32 v[70:71], 0
	v_mov_b64_e32 v[72:73], 0
	v_mov_b64_e32 v[74:75], 0
	v_mov_b64_e32 v[76:77], 0
	v_mov_b64_e32 v[78:79], 0
	v_mov_b64_e32 v[80:81], 0
	v_mov_b64_e32 v[82:83], 0
	v_mov_b64_e32 v[84:85], 0
	v_mov_b64_e32 v[86:87], 0
	v_mov_b64_e32 v[88:89], 0
	v_mov_b64_e32 v[90:91], 0
	v_mov_b64_e32 v[92:93], 0
	v_mov_b64_e32 v[94:95], 0
	v_mov_b64_e32 v[96:97], 0
	v_mov_b64_e32 v[98:99], 0
	v_mov_b64_e32 v[100:101], 0
	v_mov_b64_e32 v[102:103], 0
	v_mov_b64_e32 v[104:105], 0
	v_mov_b64_e32 v[106:107], 0
	v_mov_b64_e32 v[108:109], 0
	v_mov_b64_e32 v[110:111], 0
	v_mov_b64_e32 v[112:113], 0
	v_mov_b64_e32 v[114:115], 0
	v_mov_b64_e32 v[116:117], 0
	v_mov_b64_e32 v[118:119], 0
	v_mov_b64_e32 v[120:121], 0
	v_mov_b64_e32 v[122:123], 0
	v_mov_b64_e32 v[124:125], 0
	v_mov_b64_e32 v[126:127], 0

; DI void gemm_phase(LAS unsigned char* lds, const Gemm g, const StaticOrder& S, const Epi& E) {
;     ...
;         for (int a = 0; a < 2; ++a)
; #pragma unroll
;             for (int b = 0; b < 2; ++b)
; #pragma unroll
;                 for (int m = 0; m < 4; ++m)
; #pragma unroll
;                     for (int n = 0; n < 2; ++n) acc[a][b][m][n] = (f32x4){0.f, 0.f, 0.f, 0.f};
.LBB0_1019:
	s_ashr_i32 s17, s16, 31
	s_lshl_b64 s[18:19], s[16:17], 20
	s_add_u32 s18, s62, s18
	s_addc_u32 s19, s63, s19
	s_and_b64 s[20:21], s[4:5], exec
	s_cselect_b32 s17, s19, s25
	s_cselect_b32 s41, s18, s24
	s_ashr_i32 s15, s14, 31
	s_lshl_b64 s[20:21], s[14:15], 20
	s_add_u32 s20, s0, s20
	s_addc_u32 s21, s1, s21
	s_and_b64 s[28:29], s[4:5], exec
	s_cselect_b32 s15, s21, s27
	s_cselect_b32 s42, s20, s26
	s_add_u32 s24, s24, 0x80080
	s_addc_u32 s25, s25, 0
	s_add_u32 s43, s26, 0x100
	v_mov_b32_e32 v0, 0
	s_addc_u32 s48, s27, 0
	s_mov_b32 s49, -2
	v_mov_b64_e32 v[0:1], 0
	v_mov_b64_e32 v[2:3], 0
	v_mov_b64_e32 v[4:5], 0
	v_mov_b64_e32 v[6:7], 0
	v_mov_b64_e32 v[8:9], 0
	v_mov_b64_e32 v[10:11], 0
	v_mov_b64_e32 v[12:13], 0
	v_mov_b64_e32 v[14:15], 0
	v_mov_b64_e32 v[16:17], 0
	v_mov_b64_e32 v[18:19], 0
	v_mov_b64_e32 v[20:21], 0
	v_mov_b64_e32 v[22:23], 0
	v_mov_b64_e32 v[24:25], 0
	v_mov_b64_e32 v[26:27], 0
	v_mov_b64_e32 v[28:29], 0
	v_mov_b64_e32 v[30:31], 0
	v_mov_b64_e32 v[32:33], 0
	v_mov_b64_e32 v[34:35], 0
	v_mov_b64_e32 v[36:37], 0
	v_mov_b64_e32 v[38:39], 0
	v_mov_b64_e32 v[40:41], 0
	v_mov_b64_e32 v[42:43], 0
	v_mov_b64_e32 v[44:45], 0
	v_mov_b64_e32 v[46:47], 0
	v_mov_b64_e32 v[48:49], 0
	v_mov_b64_e32 v[50:51], 0
	v_mov_b64_e32 v[52:53], 0
	v_mov_b64_e32 v[54:55], 0
	v_mov_b64_e32 v[56:57], 0
	v_mov_b64_e32 v[58:59], 0
	v_mov_b64_e32 v[60:61], 0
	v_mov_b64_e32 v[62:63], 0
	v_mov_b64_e32 v[64:65], 0
	v_mov_b64_e32 v[66:67], 0
	v_mov_b64_e32 v[68:69], 0
	v_mov_b64_e32 v[70:71], 0
	v_mov_b64_e32 v[72:73], 0
	v_mov_b64_e32 v[74:75], 0
	v_mov_b64_e32 v[76:77], 0
	v_mov_b64_e32 v[78:79], 0
	v_mov_b64_e32 v[80:81], 0
	v_mov_b64_e32 v[82:83], 0
	v_mov_b64_e32 v[84:85], 0
	v_mov_b64_e32 v[86:87], 0
	v_mov_b64_e32 v[88:89], 0
	v_mov_b64_e32 v[90:91], 0
	v_mov_b64_e32 v[92:93], 0
	v_mov_b64_e32 v[94:95], 0
	v_mov_b64_e32 v[96:97], 0
	v_mov_b64_e32 v[98:99], 0
	v_mov_b64_e32 v[100:101], 0
	v_mov_b64_e32 v[102:103], 0
	v_mov_b64_e32 v[104:105], 0
	v_mov_b64_e32 v[106:107], 0
	v_mov_b64_e32 v[108:109], 0
	v_mov_b64_e32 v[110:111], 0
	v_mov_b64_e32 v[112:113], 0
	v_mov_b64_e32 v[114:115], 0
	v_mov_b64_e32 v[116:117], 0
	v_mov_b64_e32 v[118:119], 0
	v_mov_b64_e32 v[120:121], 0
	v_mov_b64_e32 v[122:123], 0
	v_mov_b64_e32 v[124:125], 0
	v_mov_b64_e32 v[126:127], 0

; DI void gemm_phase(LAS unsigned char* lds, const Gemm g, const StaticOrder& S, const Epi& E) {
;     ...
;         for (int a = 0; a < 2; ++a)
; #pragma unroll
;             for (int b = 0; b < 2; ++b)
; #pragma unroll
;                 for (int m = 0; m < 4; ++m)
; #pragma unroll
;                     for (int n = 0; n < 2; ++n) acc[a][b][m][n] = (f32x4){0.f, 0.f, 0.f, 0.f};
.LBB0_1100:
	s_add_u32 s51, s26, 0x100
	v_mov_b32_e32 v0, 0
	s_addc_u32 s52, s27, 0
	s_mov_b32 s53, -2
	v_mov_b64_e32 v[0:1], 0
	v_mov_b64_e32 v[2:3], 0
	v_mov_b64_e32 v[4:5], 0
	v_mov_b64_e32 v[6:7], 0
	v_mov_b64_e32 v[8:9], 0
	v_mov_b64_e32 v[10:11], 0
	v_mov_b64_e32 v[12:13], 0
	v_mov_b64_e32 v[14:15], 0
	v_mov_b64_e32 v[16:17], 0
	v_mov_b64_e32 v[18:19], 0
	v_mov_b64_e32 v[20:21], 0
	v_mov_b64_e32 v[22:23], 0
	v_mov_b64_e32 v[24:25], 0
	v_mov_b64_e32 v[26:27], 0
	v_mov_b64_e32 v[28:29], 0
	v_mov_b64_e32 v[30:31], 0
	v_mov_b64_e32 v[32:33], 0
	v_mov_b64_e32 v[34:35], 0
	v_mov_b64_e32 v[36:37], 0
	v_mov_b64_e32 v[38:39], 0
	v_mov_b64_e32 v[40:41], 0
	v_mov_b64_e32 v[42:43], 0
	v_mov_b64_e32 v[44:45], 0
	v_mov_b64_e32 v[46:47], 0
	v_mov_b64_e32 v[48:49], 0
	v_mov_b64_e32 v[50:51], 0
	v_mov_b64_e32 v[52:53], 0
	v_mov_b64_e32 v[54:55], 0
	v_mov_b64_e32 v[56:57], 0
	v_mov_b64_e32 v[58:59], 0
	v_mov_b64_e32 v[60:61], 0
	v_mov_b64_e32 v[62:63], 0
	v_mov_b64_e32 v[64:65], 0
	v_mov_b64_e32 v[66:67], 0
	v_mov_b64_e32 v[68:69], 0
	v_mov_b64_e32 v[70:71], 0
	v_mov_b64_e32 v[72:73], 0
	v_mov_b64_e32 v[74:75], 0
	v_mov_b64_e32 v[76:77], 0
	v_mov_b64_e32 v[78:79], 0
	v_mov_b64_e32 v[80:81], 0
	v_mov_b64_e32 v[82:83], 0
	v_mov_b64_e32 v[84:85], 0
	v_mov_b64_e32 v[86:87], 0
	v_mov_b64_e32 v[88:89], 0
	v_mov_b64_e32 v[90:91], 0
	v_mov_b64_e32 v[92:93], 0
	v_mov_b64_e32 v[94:95], 0
	v_mov_b64_e32 v[96:97], 0
	v_mov_b64_e32 v[98:99], 0
	v_mov_b64_e32 v[100:101], 0
	v_mov_b64_e32 v[102:103], 0
	v_mov_b64_e32 v[104:105], 0
	v_mov_b64_e32 v[106:107], 0
	v_mov_b64_e32 v[108:109], 0
	v_mov_b64_e32 v[110:111], 0
	v_mov_b64_e32 v[112:113], 0
	v_mov_b64_e32 v[114:115], 0
	v_mov_b64_e32 v[116:117], 0
	v_mov_b64_e32 v[118:119], 0
	v_mov_b64_e32 v[120:121], 0
	v_mov_b64_e32 v[122:123], 0
	v_mov_b64_e32 v[124:125], 0
	v_mov_b64_e32 v[126:127], 0
